# grid barrier: last XCD leader releases all XCDs' generation words directly (one less hop)
# speedup vs baseline: 1.0009x; 1.0009x over previous
.LBB0_132:
	s_or_b64 exec, exec, s[12:13]
	v_cvt_f32_u32_e32 v5, v2
	s_waitcnt vmcnt(0)
	v_readfirstlane_b32 s2, v4
	s_add_u32 s12, s82, 0x7500
	s_addc_u32 s13, s83, 0
	v_rcp_iflag_f32_e32 v5, v5
	v_add_u32_e32 v3, s2, v3
	v_add_u32_e32 v6, 1, v3
	s_mov_b64 s[16:17], -1
	v_mul_f32_e32 v4, 0x4f7ffffe, v5
	v_cvt_u32_f32_e32 v4, v4
	v_sub_u32_e32 v5, 0, v2
	v_mul_lo_u32 v5, v5, v4
	v_mul_hi_u32 v5, v4, v5
	v_add_u32_e32 v4, v4, v5
	v_mul_hi_u32 v4, v3, v4
	v_mul_lo_u32 v5, v4, v2
	v_sub_u32_e32 v3, v3, v5
	v_add_u32_e32 v7, 1, v4
	v_cmp_ge_u32_e32 vcc, v3, v2
	v_sub_u32_e32 v5, v3, v2
	s_nop 0
	v_cndmask_b32_e32 v4, v4, v7, vcc
	v_cndmask_b32_e32 v3, v3, v5, vcc
	v_add_u32_e32 v5, 1, v4
	v_cmp_ge_u32_e32 vcc, v3, v2
	s_nop 1
	v_cndmask_b32_e32 v4, v4, v5, vcc
	v_mul_lo_u32 v3, v2, v4
	v_add_u32_e32 v2, v3, v2
	v_cmp_ne_u32_e32 vcc, v6, v2
	v_mov_b64_e32 v[2:3], s[12:13]
	s_and_saveexec_b64 s[6:7], vcc
	s_cbranch_execnz .Lb1spin_0
	s_or_b64 exec, exec, s[6:7]
	v_mov_b32_e32 v4, 1
	global_atomic_add v[2:3], v4, off
	v_mov_b32_e32 v2, 0x2400
	global_atomic_add v2, v4, s[84:85]
	v_mov_b32_e32 v3, 0x2500
	global_atomic_add v3, v4, s[84:85]
	v_mov_b32_e32 v2, 0x2600
	global_atomic_add v2, v4, s[84:85]
	v_mov_b32_e32 v3, 0x2700
	global_atomic_add v3, v4, s[84:85]
	v_mov_b32_e32 v2, 0x2800
	global_atomic_add v2, v4, s[84:85]
	v_mov_b32_e32 v3, 0x2900
	global_atomic_add v3, v4, s[84:85]
	v_mov_b32_e32 v2, 0x2a00
	global_atomic_add v2, v4, s[84:85]
	v_mov_b32_e32 v3, 0x2b00
	global_atomic_add v3, v4, s[84:85]
	v_mov_b32_e32 v2, 0x2c00
	global_atomic_add v2, v4, s[84:85]
	v_mov_b32_e32 v3, 0x2d00
	global_atomic_add v3, v4, s[84:85]
	v_mov_b32_e32 v2, 0x2e00
	global_atomic_add v2, v4, s[84:85]
	v_mov_b32_e32 v3, 0x2f00
	global_atomic_add v3, v4, s[84:85]
	v_mov_b32_e32 v2, 0x3000
	global_atomic_add v2, v4, s[84:85]
	v_mov_b32_e32 v3, 0x3100
	global_atomic_add v3, v4, s[84:85]
	v_mov_b32_e32 v2, 0x3200
	global_atomic_add v2, v4, s[84:85]
	v_mov_b32_e32 v3, 0x3300
	global_atomic_add v3, v4, s[84:85]
	buffer_inv sc1
	s_waitcnt vmcnt(0)
	s_branch .LBB0_147
.Lb1spin_0:
	v_mov_b32_e32 v2, 0
	global_load_dword v3, v2, s[12:13] sc1
	s_mov_b64 s[20:21], 0
	s_waitcnt vmcnt(0)
	v_cmp_eq_u32_e32 vcc, v3, v4
	s_and_saveexec_b64 s[18:19], vcc
	s_cbranch_execz .LBB0_143
	s_add_u32 s16, s82, 0x4200
	s_addc_u32 s17, s83, 0
	s_mov_b32 s2, 1
	s_branch .LBB0_136

.LBB0_146:
	s_or_b64 exec, exec, s[6:7]
	v_mov_b32_e32 v2, 0x2000
	v_mov_b32_e32 v3, 1
	s_waitcnt vmcnt(0)
	buffer_inv sc1
	s_waitcnt vmcnt(0)

.LBB0_460:
	s_or_b64 exec, exec, s[8:9]
	v_cvt_f32_u32_e32 v5, v2
	s_waitcnt vmcnt(0)
	v_readfirstlane_b32 s2, v4
	s_add_u32 s8, s82, 0x7500
	s_addc_u32 s9, s83, 0
	v_rcp_iflag_f32_e32 v5, v5
	v_add_u32_e32 v3, s2, v3
	v_add_u32_e32 v6, 1, v3
	s_mov_b64 s[10:11], -1
	v_mul_f32_e32 v4, 0x4f7ffffe, v5
	v_cvt_u32_f32_e32 v4, v4
	v_sub_u32_e32 v5, 0, v2
	v_mul_lo_u32 v5, v5, v4
	v_mul_hi_u32 v5, v4, v5
	v_add_u32_e32 v4, v4, v5
	v_mul_hi_u32 v4, v3, v4
	v_mul_lo_u32 v5, v4, v2
	v_sub_u32_e32 v3, v3, v5
	v_add_u32_e32 v7, 1, v4
	v_cmp_ge_u32_e32 vcc, v3, v2
	v_sub_u32_e32 v5, v3, v2
	s_nop 0
	v_cndmask_b32_e32 v4, v4, v7, vcc
	v_cndmask_b32_e32 v3, v3, v5, vcc
	v_add_u32_e32 v5, 1, v4
	v_cmp_ge_u32_e32 vcc, v3, v2
	s_nop 1
	v_cndmask_b32_e32 v4, v4, v5, vcc
	v_mul_lo_u32 v3, v2, v4
	v_add_u32_e32 v2, v3, v2
	v_cmp_ne_u32_e32 vcc, v6, v2
	v_mov_b64_e32 v[2:3], s[8:9]
	s_and_saveexec_b64 s[6:7], vcc
	s_cbranch_execnz .Lb1spin_5
	s_or_b64 exec, exec, s[6:7]
	v_mov_b32_e32 v4, 1
	global_atomic_add v[2:3], v4, off
	v_mov_b32_e32 v2, 0x2400
	global_atomic_add v2, v4, s[84:85]
	v_mov_b32_e32 v3, 0x2500
	global_atomic_add v3, v4, s[84:85]
	v_mov_b32_e32 v2, 0x2600
	global_atomic_add v2, v4, s[84:85]
	v_mov_b32_e32 v3, 0x2700
	global_atomic_add v3, v4, s[84:85]
	v_mov_b32_e32 v2, 0x2800
	global_atomic_add v2, v4, s[84:85]
	v_mov_b32_e32 v3, 0x2900
	global_atomic_add v3, v4, s[84:85]
	v_mov_b32_e32 v2, 0x2a00
	global_atomic_add v2, v4, s[84:85]
	v_mov_b32_e32 v3, 0x2b00
	global_atomic_add v3, v4, s[84:85]
	v_mov_b32_e32 v2, 0x2c00
	global_atomic_add v2, v4, s[84:85]
	v_mov_b32_e32 v3, 0x2d00
	global_atomic_add v3, v4, s[84:85]
	v_mov_b32_e32 v2, 0x2e00
	global_atomic_add v2, v4, s[84:85]
	v_mov_b32_e32 v3, 0x2f00
	global_atomic_add v3, v4, s[84:85]
	v_mov_b32_e32 v2, 0x3000
	global_atomic_add v2, v4, s[84:85]
	v_mov_b32_e32 v3, 0x3100
	global_atomic_add v3, v4, s[84:85]
	v_mov_b32_e32 v2, 0x3200
	global_atomic_add v2, v4, s[84:85]
	v_mov_b32_e32 v3, 0x3300
	global_atomic_add v3, v4, s[84:85]
	buffer_inv sc1
	s_waitcnt vmcnt(0)
	s_branch .LBB0_475
.Lb1spin_5:
	v_mov_b32_e32 v2, 0
	global_load_dword v3, v2, s[8:9] sc1
	s_mov_b64 s[16:17], 0
	s_waitcnt vmcnt(0)
	v_cmp_eq_u32_e32 vcc, v3, v4
	s_and_saveexec_b64 s[12:13], vcc
	s_cbranch_execz .LBB0_471
	s_add_u32 s10, s82, 0x4200
	s_addc_u32 s11, s83, 0
	s_mov_b32 s2, 1
	s_branch .LBB0_464

.LBB0_662:
	s_or_b64 exec, exec, s[8:9]
	v_cvt_f32_u32_e32 v4, v1
	s_waitcnt vmcnt(0)
	v_readfirstlane_b32 s2, v3
	s_add_u32 s8, s82, 0x7500
	s_addc_u32 s9, s83, 0
	v_rcp_iflag_f32_e32 v4, v4
	v_add_u32_e32 v2, s2, v2
	v_add_u32_e32 v5, 1, v2
	s_mov_b64 s[10:11], -1
	v_mul_f32_e32 v3, 0x4f7ffffe, v4
	v_cvt_u32_f32_e32 v3, v3
	v_sub_u32_e32 v4, 0, v1
	v_mul_lo_u32 v4, v4, v3
	v_mul_hi_u32 v4, v3, v4
	v_add_u32_e32 v3, v3, v4
	v_mul_hi_u32 v3, v2, v3
	v_mul_lo_u32 v4, v3, v1
	v_sub_u32_e32 v2, v2, v4
	v_add_u32_e32 v6, 1, v3
	v_cmp_ge_u32_e32 vcc, v2, v1
	v_sub_u32_e32 v4, v2, v1
	s_nop 0
	v_cndmask_b32_e32 v3, v3, v6, vcc
	v_cndmask_b32_e32 v2, v2, v4, vcc
	v_add_u32_e32 v4, 1, v3
	v_cmp_ge_u32_e32 vcc, v2, v1
	s_nop 1
	v_cndmask_b32_e32 v4, v3, v4, vcc
	v_mul_lo_u32 v2, v1, v4
	v_add_u32_e32 v1, v2, v1
	v_cmp_ne_u32_e32 vcc, v5, v1
	v_mov_b64_e32 v[2:3], s[8:9]
	s_and_saveexec_b64 s[6:7], vcc
	s_cbranch_execnz .Lb1spin_8
	s_or_b64 exec, exec, s[6:7]
	v_mov_b32_e32 v1, 1
	global_atomic_add v[2:3], v1, off
	v_mov_b32_e32 v2, 0x2400
	global_atomic_add v2, v1, s[84:85]
	v_mov_b32_e32 v3, 0x2500
	global_atomic_add v3, v1, s[84:85]
	v_mov_b32_e32 v2, 0x2600
	global_atomic_add v2, v1, s[84:85]
	v_mov_b32_e32 v3, 0x2700
	global_atomic_add v3, v1, s[84:85]
	v_mov_b32_e32 v2, 0x2800
	global_atomic_add v2, v1, s[84:85]
	v_mov_b32_e32 v3, 0x2900
	global_atomic_add v3, v1, s[84:85]
	v_mov_b32_e32 v2, 0x2a00
	global_atomic_add v2, v1, s[84:85]
	v_mov_b32_e32 v3, 0x2b00
	global_atomic_add v3, v1, s[84:85]
	v_mov_b32_e32 v2, 0x2c00
	global_atomic_add v2, v1, s[84:85]
	v_mov_b32_e32 v3, 0x2d00
	global_atomic_add v3, v1, s[84:85]
	v_mov_b32_e32 v2, 0x2e00
	global_atomic_add v2, v1, s[84:85]
	v_mov_b32_e32 v3, 0x2f00
	global_atomic_add v3, v1, s[84:85]
	v_mov_b32_e32 v2, 0x3000
	global_atomic_add v2, v1, s[84:85]
	v_mov_b32_e32 v3, 0x3100
	global_atomic_add v3, v1, s[84:85]
	v_mov_b32_e32 v2, 0x3200
	global_atomic_add v2, v1, s[84:85]
	v_mov_b32_e32 v3, 0x3300
	global_atomic_add v3, v1, s[84:85]
	buffer_inv sc1
	s_waitcnt vmcnt(0)
	s_branch .LBB0_677
.Lb1spin_8:
	v_mov_b32_e32 v1, 0
	global_load_dword v2, v1, s[8:9] sc1
	s_mov_b64 s[16:17], 0
	s_waitcnt vmcnt(0)
	v_cmp_eq_u32_e32 vcc, v2, v4
	s_and_saveexec_b64 s[12:13], vcc
	s_cbranch_execz .LBB0_673
	s_add_u32 s10, s82, 0x4200
	s_addc_u32 s11, s83, 0
	s_mov_b32 s2, 1
	s_branch .LBB0_666

.LBB0_676:
	s_or_b64 exec, exec, s[6:7]
	v_mov_b32_e32 v1, 0x2000
	v_mov_b32_e32 v2, 1
	s_waitcnt vmcnt(0)
	buffer_inv sc1
	s_waitcnt vmcnt(0)

.Lb1spin_10:
	v_mov_b32_e32 v1, 0
	global_load_dword v2, v1, s[8:9] sc1
	s_mov_b64 s[14:15], 0
	s_waitcnt vmcnt(0)
	v_cmp_eq_u32_e32 vcc, v2, v4
	s_and_saveexec_b64 s[12:13], vcc
	s_cbranch_execz .LBB0_881
	s_add_u32 s10, s82, 0x4200
	s_addc_u32 s11, s83, 0
	s_mov_b32 s2, 1
	s_branch .LBB0_874

.LBB0_2786:
	s_or_b64 exec, exec, s[6:7]
	v_cvt_f32_u32_e32 v3, v0
	s_waitcnt vmcnt(0)
	v_readfirstlane_b32 s4, v2
	s_add_u32 s6, s82, 0x7500
	s_addc_u32 s7, s83, 0
	v_rcp_iflag_f32_e32 v3, v3
	v_add_u32_e32 v1, s4, v1
	v_add_u32_e32 v4, 1, v1
	s_mov_b64 s[8:9], -1
	v_mul_f32_e32 v2, 0x4f7ffffe, v3
	v_cvt_u32_f32_e32 v2, v2
	v_sub_u32_e32 v3, 0, v0
	v_mul_lo_u32 v3, v3, v2
	v_mul_hi_u32 v3, v2, v3
	v_add_u32_e32 v2, v2, v3
	v_mul_hi_u32 v2, v1, v2
	v_mul_lo_u32 v3, v2, v0
	v_sub_u32_e32 v1, v1, v3
	v_add_u32_e32 v5, 1, v2
	v_cmp_ge_u32_e32 vcc, v1, v0
	v_sub_u32_e32 v3, v1, v0
	s_nop 0
	v_cndmask_b32_e32 v2, v2, v5, vcc
	v_cndmask_b32_e32 v1, v1, v3, vcc
	v_add_u32_e32 v3, 1, v2
	v_cmp_ge_u32_e32 vcc, v1, v0
	s_nop 1
	v_cndmask_b32_e32 v2, v2, v3, vcc
	v_mul_lo_u32 v1, v0, v2
	v_add_u32_e32 v0, v1, v0
	v_cmp_ne_u32_e32 vcc, v4, v0
	v_mov_b64_e32 v[0:1], s[6:7]
	s_and_saveexec_b64 s[4:5], vcc
	s_cbranch_execnz .Lb1spin_35
	s_or_b64 exec, exec, s[4:5]
	v_mov_b32_e32 v2, 1
	global_atomic_add v[0:1], v2, off
	v_mov_b32_e32 v0, 0x2400
	global_atomic_add v0, v2, s[84:85]
	v_mov_b32_e32 v1, 0x2500
	global_atomic_add v1, v2, s[84:85]
	v_mov_b32_e32 v0, 0x2600
	global_atomic_add v0, v2, s[84:85]
	v_mov_b32_e32 v1, 0x2700
	global_atomic_add v1, v2, s[84:85]
	v_mov_b32_e32 v0, 0x2800
	global_atomic_add v0, v2, s[84:85]
	v_mov_b32_e32 v1, 0x2900
	global_atomic_add v1, v2, s[84:85]
	v_mov_b32_e32 v0, 0x2a00
	global_atomic_add v0, v2, s[84:85]
	v_mov_b32_e32 v1, 0x2b00
	global_atomic_add v1, v2, s[84:85]
	v_mov_b32_e32 v0, 0x2c00
	global_atomic_add v0, v2, s[84:85]
	v_mov_b32_e32 v1, 0x2d00
	global_atomic_add v1, v2, s[84:85]
	v_mov_b32_e32 v0, 0x2e00
	global_atomic_add v0, v2, s[84:85]
	v_mov_b32_e32 v1, 0x2f00
	global_atomic_add v1, v2, s[84:85]
	v_mov_b32_e32 v0, 0x3000
	global_atomic_add v0, v2, s[84:85]
	v_mov_b32_e32 v1, 0x3100
	global_atomic_add v1, v2, s[84:85]
	v_mov_b32_e32 v0, 0x3200
	global_atomic_add v0, v2, s[84:85]
	v_mov_b32_e32 v1, 0x3300
	global_atomic_add v1, v2, s[84:85]
	buffer_inv sc1
	s_waitcnt vmcnt(0)
	s_branch .LBB0_2801
.Lb1spin_35:
	v_mov_b32_e32 v0, 0
	global_load_dword v1, v0, s[6:7] sc1
	s_mov_b64 s[12:13], 0
	s_waitcnt vmcnt(0)
	v_cmp_eq_u32_e32 vcc, v1, v2
	s_and_saveexec_b64 s[10:11], vcc
	s_cbranch_execz .LBB0_2797
	s_add_u32 s8, s82, 0x4200
	s_addc_u32 s9, s83, 0
	s_mov_b32 s22, 1
	s_branch .LBB0_2790

.LBB0_2800:
	s_or_b64 exec, exec, s[4:5]
	v_mov_b32_e32 v0, 0x2000
	v_mov_b32_e32 v1, 1
	s_waitcnt vmcnt(0)
	buffer_inv sc1
	s_waitcnt vmcnt(0)
